# byte-placement trial: inproj phase code shifted by 48 bytes (K-loop head at a 64-byte boundary), later code kept in place
# speedup vs baseline: 1.0033x; 1.0028x over previous
; DI void phase_inproj(const Params& p, int l, char* smem, int tid) {
;     ...
;   for (int it = blockIdx.x; it < 272 * 24; it += gridDim.x) {
;     const int mt = it / 24, nt = it % 24, m0 = mt * 128, n0 = nt * 128;
;     f32x16 acc[2][2]; zero_acc<2>(acc);
;     gemm_main<2>(p.xn + (size_t)m0 * 1024, 1024, Wt + (size_t)n0 * 1024, 1024, 1024, acc, s, tid);
.Lipx_flat:
	s_movk_i32 s2, 0x1980
	s_bitcmp1_b32 s17, 31
	s_cselect_b32 s2, 0x330, s2
	s_cmp_lt_u32 s12, s2
	s_cbranch_scc0 .Lip_done
	s_mul_hi_u32 s0, s12, 0xaaaaaaab
	s_bitcmp1_b32 s17, 31
	s_cselect_b32 s2, 2, 4
	s_lshr_b32 s0, s0, s2
	s_bitcmp1_b32 s17, 31
	s_cselect_b32 s2, 6, 24
	s_mul_i32 s2, s0, s2
	s_sub_u32 s1, s12, s2
	s_bfe_u32 s2, s17, 0x80012
	s_add_u32 s1, s1, s2
	s_bitcmp1_b32 s17, 31
	s_cselect_b32 s2, 1, 0
	s_lshl_b32 s0, s0, s2
	s_bfe_u32 s2, s17, 0x8000a
	s_add_u32 s0, s0, s2
	s_lshl_b32 s2, s0, 18
	s_add_u32 s4, s96, s2
	s_addc_u32 s5, s97, 0
	s_lshl_b32 s2, s1, 18
	s_add_u32 s8, s14, s2
	s_addc_u32 s9, s15, 0
	s_add_u32 m0, s10, 0x0
	s_nop 0
	global_load_lds_dwordx4 v98, s[4:5]
	s_add_u32 m0, s10, 0x400
	s_nop 0
	global_load_lds_dwordx4 v99, s[4:5]
	s_add_u32 m0, s10, 0x800
	s_nop 0
	global_load_lds_dwordx4 v100, s[4:5]
	s_add_u32 m0, s10, 0xc00
	s_nop 0
	global_load_lds_dwordx4 v101, s[4:5]
	s_add_u32 m0, s10, 0x4000
	s_nop 0
	global_load_lds_dwordx4 v98, s[8:9]
	s_add_u32 m0, s10, 0x4400
	s_nop 0
	global_load_lds_dwordx4 v99, s[8:9]
	s_add_u32 m0, s10, 0x4800
	s_nop 0
	global_load_lds_dwordx4 v100, s[8:9]
	s_add_u32 m0, s10, 0x4c00
	s_nop 0
	global_load_lds_dwordx4 v101, s[8:9]
	s_add_u32 s4, s4, 128
	s_addc_u32 s5, s5, 0
	s_add_u32 s8, s8, 128
	s_addc_u32 s9, s9, 0
	s_nop 0
	s_nop 0
	s_nop 0
	s_nop 0
	s_nop 0
	s_nop 0
	s_nop 0
	s_nop 0
	s_nop 0
	s_nop 0
	s_nop 0
	s_nop 0
